# RG-LRU chunk loop: loop-top vmcnt(0) relaxed to vmcnt(8) so the previous chunk's eight output stores no longer drain before the next chunk starts
# speedup vs baseline: 1.0036x; 1.0036x over previous
; __device__ __forceinline__ float bflo(unsigned w) { return __uint_as_float(w << 16); }
; __device__ __forceinline__ float bfhi(unsigned w) { return __uint_as_float(w & 0xffff0000u); }
; __device__ __forceinline__ unsigned pk2(float lo, float hi) { const g_f32x2 f = {lo, hi}; return __builtin_bit_cast(unsigned, __builtin_convertvector(f, g_bf16x2)); }
; #define LASP __attribute__((address_space(3)))
; #define LRU_LOAD(tq0) do { _Pragma("unroll") for (int jj = 0; jj < 4; ++jj) { const int tt = (tq0) + tr - 1 + jj; \
;             nx[jj] = (tt >= 0 && tt < len) ? *(const u32x4_t*)(Ub + (size_t)tt * NINP) : (u32x4_t){0u, 0u, 0u, 0u}; } } while (0)
; __device__ __forceinline__ void p3_lru2(int l, unsigned char* smem, int item) {
;     ...
;         for (int ci = 0; ci < nch; ++ci) {
;             const int t0 = (dir ? nch - 1 - ci : ci) * 64;
;             { float xv[8];
; #pragma unroll
;               for (int e = 0; e < 8; ++e) xv[e] = cb[e];
; #pragma unroll
;               for (int jj = 0; jj < 4; ++jj) { const u32x4_t w = nx[jj];
;                   xv[0] += cw[jj][0] * bflo(w.x); xv[1] += cw[jj][1] * bfhi(w.x); xv[2] += cw[jj][2] * bflo(w.y); xv[3] += cw[jj][3] * bfhi(w.y);
;                   xv[4] += cw[jj][4] * bflo(w.z); xv[5] += cw[jj][5] * bfhi(w.z); xv[6] += cw[jj][6] * bflo(w.w); xv[7] += cw[jj][7] * bfhi(w.w); }
;               u32x4_t pk; pk.x = pk2(xv[0], xv[1]); pk.y = pk2(xv[2], xv[3]); pk.z = pk2(xv[4], xv[5]); pk.w = pk2(xv[6], xv[7]);
;               *(LASP u32x4_t*)(ls + O_XS + tr * 144 + c8 * 16) = pk;
;               *(LASP f32x4_t*)(xcf + tr * 64 + c8 * 8) = (f32x4_t){xv[0], xv[1], xv[2], xv[3]};
;               *(LASP f32x4_t*)(xcf + tr * 64 + c8 * 8 + 4) = (f32x4_t){xv[4], xv[5], xv[6], xv[7]}; }
;             if (ci + 1 < nch) LRU_LOAD((dir ? nch - 2 - ci : ci + 1) * 64);
.LBB0_759:
	s_or_b64 exec, exec, s[16:17]
	s_lshr_b32 s13, s11, 6
	s_xor_b64 s[46:47], s[2:3], -1
	s_add_i32 s26, s13, -2
	s_mov_b32 s5, 0
	s_waitcnt vmcnt(0)
.LBB0_760:
	s_waitcnt vmcnt(8)
	v_lshlrev_b32_e32 v2, 16, v52
	v_and_b32_e32 v3, 0xffff0000, v52
	v_pk_fma_f32 v[2:3], v[8:9], v[2:3], v[40:41]
	v_lshlrev_b32_e32 v68, 16, v56
	v_and_b32_e32 v69, 0xffff0000, v56
	v_pk_fma_f32 v[2:3], v[16:17], v[68:69], v[2:3]
	v_lshlrev_b32_e32 v68, 16, v60
	v_and_b32_e32 v69, 0xffff0000, v60
	v_pk_fma_f32 v[2:3], v[24:25], v[68:69], v[2:3]
	v_lshlrev_b32_e32 v68, 16, v64
	v_and_b32_e32 v69, 0xffff0000, v64
	v_pk_fma_f32 v[68:69], v[32:33], v[68:69], v[2:3]
	v_lshlrev_b32_e32 v2, 16, v53
	v_and_b32_e32 v3, 0xffff0000, v53
	v_pk_fma_f32 v[2:3], v[10:11], v[2:3], v[42:43]
	v_lshlrev_b32_e32 v70, 16, v57
	v_and_b32_e32 v71, 0xffff0000, v57
	v_pk_fma_f32 v[2:3], v[18:19], v[70:71], v[2:3]
	v_lshlrev_b32_e32 v70, 16, v61
	v_and_b32_e32 v71, 0xffff0000, v61
	v_pk_fma_f32 v[2:3], v[26:27], v[70:71], v[2:3]
	v_lshlrev_b32_e32 v70, 16, v65
	v_and_b32_e32 v71, 0xffff0000, v65
	v_pk_fma_f32 v[70:71], v[34:35], v[70:71], v[2:3]
	v_lshlrev_b32_e32 v2, 16, v54
	v_and_b32_e32 v3, 0xffff0000, v54
	v_pk_fma_f32 v[2:3], v[4:5], v[2:3], v[36:37]
	v_lshlrev_b32_e32 v72, 16, v58
	v_and_b32_e32 v73, 0xffff0000, v58
	v_pk_fma_f32 v[2:3], v[12:13], v[72:73], v[2:3]
	v_lshlrev_b32_e32 v72, 16, v62
	v_and_b32_e32 v73, 0xffff0000, v62
	v_pk_fma_f32 v[2:3], v[20:21], v[72:73], v[2:3]
	v_lshlrev_b32_e32 v72, 16, v66
	v_and_b32_e32 v73, 0xffff0000, v66
	v_pk_fma_f32 v[72:73], v[28:29], v[72:73], v[2:3]
	v_lshlrev_b32_e32 v2, 16, v55
	v_and_b32_e32 v3, 0xffff0000, v55
	v_pk_fma_f32 v[2:3], v[6:7], v[2:3], v[38:39]
	v_lshlrev_b32_e32 v74, 16, v59
	v_and_b32_e32 v75, 0xffff0000, v59
	v_pk_fma_f32 v[2:3], v[14:15], v[74:75], v[2:3]
	v_lshlrev_b32_e32 v74, 16, v63
	v_and_b32_e32 v75, 0xffff0000, v63
	v_pk_fma_f32 v[2:3], v[22:23], v[74:75], v[2:3]
	v_lshlrev_b32_e32 v74, 16, v67
	v_and_b32_e32 v75, 0xffff0000, v67
	v_pk_fma_f32 v[74:75], v[30:31], v[74:75], v[2:3]
	s_add_i32 s27, s5, 1
	v_cvt_pk_bf16_f32 v76, v68, v69
	v_cvt_pk_bf16_f32 v77, v70, v71
	v_cvt_pk_bf16_f32 v78, v72, v73
	v_cvt_pk_bf16_f32 v79, v74, v75
	s_cmp_ge_u32 s27, s13
	ds_write_b128 v127, v[76:79]
	ds_write_b128 v100, v[68:71] offset:9216
	ds_write_b128 v100, v[72:75] offset:9232
	s_cbranch_scc1 .LBB0_770
	s_sub_i32 s16, s26, s5
	s_and_b64 s[2:3], s[40:41], exec
	s_cselect_b32 s2, s27, s16
	s_lshl_b32 s16, s2, 6
	v_mov_b32_e32 v56, 0
	v_mov_b32_e32 v57, v0
	v_add_u32_e32 v64, s16, v99
	v_mov_b32_e32 v58, v0
	v_mov_b32_e32 v59, v0
	v_mov_b64_e32 v[52:53], v[56:57]
	v_cmp_gt_u32_e32 vcc, s11, v64
	v_mov_b64_e32 v[54:55], v[58:59]
	s_and_saveexec_b64 s[2:3], vcc
	s_cbranch_execz .LBB0_763
	v_mad_u64_u32 v[2:3], s[28:29], v64, s90, v[90:91]
	global_load_dwordx4 v[52:55], v[2:3], off offset:3136
